# v3 + attention item loop: latch waits vmcnt(8) for all staged loads and the LDS-staging block no longer waits on the previous item's output stores
# speedup vs baseline: 1.0088x; 1.0088x over previous
; __device__ __forceinline__ f32x4 mfma16(bf16x8 a, bf16x8 b, f32x4 c) { return __builtin_amdgcn_mfma_f32_16x16x32_bf16(a, b, c, 0, 0, 0); }
; __device__ __forceinline__ void attn_phase(int wv, const Args& a, LAS unsigned char* lds, int w, bool dmy) {
;     ...
;     const int krow = tid >> 4, kc = tid & 15;
;     const int vc = tid >> 6, vrow = (tid & 63) * 2;
;     const int qi = 16 * wid + fr;
;     u32x4 kr[4], vr[4]; float rk[4]; bf16x8 qf[4]; float qs;
;     ...
;         const int lo2 = (wid & ~1) < 6 ? (wid & ~1) : 6;
;         f32x4 sT[10];
;         float mx = -INFINITY;
; #pragma unroll
;         for (int i = 0; i < 10; ++i) {
;             const int kt = lo2 + i, pkt = kt ^ px;
;             f32x4 ac = (f32x4){0.f, 0.f, 0.f, 0.f};
; #pragma unroll
;             for (int k4 = 0; k4 < 4; ++k4) ac = mfma16(lds_ld16(lds + AT_K + ((pkt * 16 + fr) * 136 + k4 * 32 + 8 * fq) * 2), qc[k4], ac);
; #pragma unroll
;             for (int rr = 0; rr < 4; ++rr) {
;                 const int ki = kt * 16 + 4 * fq + rr;
;                 const bool valid = (ki >= qi) && (ki <= qi + 128) && (n > 0 || ki >= 128);
;                 const float sv = valid ? ac[rr] * qscale : -INFINITY;
;                 ac[rr] = sv; mx = fmaxf(mx, sv);
.LBB0_651:
	s_add_u32 s78, s2, 0xc100000
	s_addc_u32 s79, s3, 0
	s_add_u32 s2, s2, 0x1e500000
	s_addc_u32 s3, s3, 0
	v_writelane_b32 v253, s2, 38
	v_add_u32_e32 v6, s7, v89
	v_ashrrev_i32_e32 v7, 31, v6
	v_writelane_b32 v253, s3, 39
	v_readlane_b32 s2, v252, 31
	v_readlane_b32 s3, v252, 32
	s_lshl_b64 s[2:3], s[2:3], 1
	v_writelane_b32 v253, s13, 40
	v_readlane_b32 s10, v252, 23
	v_readlane_b32 s86, v252, 24
	s_add_u32 s4, s0, s2
	v_writelane_b32 v253, s14, 41
	v_lshlrev_b64 v[2:3], s10, v[6:7]
	v_readlane_b32 s87, v252, 25
	s_addc_u32 s5, s1, s3
	v_lshlrev_b64 v[10:11], 1, v[188:189]
	v_lshl_add_u64 v[2:3], v[2:3], 0, s[86:87]
	v_writelane_b32 v253, s16, 42
	v_lshl_add_u64 v[18:19], s[4:5], 0, v[10:11]
	v_readlane_b32 s82, v252, 33
	v_mov_b64_e32 v[26:27], s[16:17]
	v_mad_u64_u32 v[4:5], s[4:5], v2, s63, v[26:27]
	v_mov_b32_e32 v8, v5
	s_add_u32 s8, s13, s2
	v_mad_u64_u32 v[8:9], s[4:5], v3, s63, v[8:9]
	v_readlane_b32 s83, v252, 34
	s_addc_u32 s9, s14, s3
	v_mov_b32_e32 v5, v8
	s_lshl_b64 s[4:5], s[82:83], 2
	v_lshl_add_u64 v[8:9], v[4:5], 0, s[4:5]
	v_add_u32_e32 v4, 32, v6
	v_ashrrev_i32_e32 v5, 31, v4
	v_lshlrev_b64 v[4:5], s10, v[4:5]
	v_lshl_add_u64 v[4:5], v[4:5], 0, s[86:87]
	v_mov_b64_e32 v[12:13], s[8:9]
	v_mad_u64_u32 v[14:15], s[8:9], v4, s63, v[26:27]
	v_mov_b32_e32 v20, v15
	v_mad_u64_u32 v[20:21], s[8:9], v5, s63, v[20:21]
	v_mov_b32_e32 v15, v20
	v_add_u32_e32 v20, 64, v6
	v_ashrrev_i32_e32 v21, 31, v20
	v_lshlrev_b64 v[20:21], s10, v[20:21]
	v_lshl_add_u64 v[20:21], v[20:21], 0, s[86:87]
	v_mad_u64_u32 v[22:23], s[8:9], v20, s63, v[26:27]
	v_add_u32_e32 v6, 0x60, v6
	v_mov_b32_e32 v24, v23
	v_ashrrev_i32_e32 v7, 31, v6
	v_mad_u64_u32 v[24:25], s[8:9], v21, s63, v[24:25]
	v_lshlrev_b64 v[6:7], s10, v[6:7]
	v_mov_b32_e32 v23, v24
	v_lshl_add_u64 v[24:25], v[6:7], 0, s[86:87]
	v_mad_u64_u32 v[6:7], s[8:9], v24, s63, v[26:27]
	v_mov_b32_e32 v28, v7
	v_mad_u64_u32 v[28:29], s[8:9], v25, s63, v[28:29]
	v_lshl_or_b32 v95, s6, 4, v85
	v_mov_b32_e32 v7, v28
	v_lshl_add_u64 v[28:29], v[6:7], 0, s[4:5]
	v_add_u32_e32 v6, s7, v95
	v_ashrrev_i32_e32 v7, 31, v6
	v_lshlrev_b64 v[6:7], s10, v[6:7]
	v_lshl_add_u64 v[6:7], v[6:7], 0, s[86:87]
	v_mov_b64_e32 v[30:31], s[78:79]
	v_mad_u64_u32 v[30:31], s[8:9], v6, s80, v[30:31]
	v_mov_b32_e32 v36, v31
	v_mad_u64_u32 v[36:37], s[8:9], v7, s80, v[36:37]
	v_mov_b32_e32 v31, v36
	v_lshl_add_u64 v[30:31], v[30:31], 0, s[2:3]
	v_mad_u64_u32 v[26:27], s[2:3], v6, s63, v[26:27]
	v_lshrrev_b32_e32 v35, 4, v38
	v_mov_b32_e32 v6, v27
	v_lshl_add_u64 v[86:87], s[0:1], 0, v[10:11]
	s_and_b32 s0, s6, -2
	v_mad_u64_u32 v[6:7], s[2:3], v7, s63, v[6:7]
	s_min_i32 s72, s0, 6
	v_lshlrev_b32_e32 v88, 2, v35
	v_mov_b32_e32 v27, v6
	v_add_u32_e32 v6, 0x80, v95
	v_lshl_or_b32 v46, s72, 4, v88
	v_cmp_lt_i32_e32 vcc, v46, v95
	v_cmp_gt_i32_e64 s[0:1], v46, v6
	v_writelane_b32 v253, s17, 43
	s_or_b64 s[0:1], vcc, s[0:1]
	v_writelane_b32 v253, s0, 44
	v_or_b32_e32 v7, 1, v46
	v_cmp_lt_i32_e32 vcc, v7, v95
	v_writelane_b32 v253, s1, 45
	v_cmp_ge_i32_e64 s[0:1], v46, v6
	s_or_b64 s[0:1], vcc, s[0:1]
	v_or_b32_e32 v47, 2, v46
	v_writelane_b32 v253, s0, 46
	v_cmp_lt_i32_e32 vcc, v47, v95
	v_or_b32_e32 v64, 3, v46
	v_writelane_b32 v253, s1, 47
	v_cmp_gt_i32_e64 s[0:1], v47, v6
	s_or_b64 s[0:1], vcc, s[0:1]
	v_cmp_lt_i32_e32 vcc, v64, v95
	v_writelane_b32 v253, s0, 48
	s_add_i32 s96, s72, 8
	v_lshl_or_b32 v102, s96, 4, v88
	v_writelane_b32 v253, s1, 49
	v_cmp_gt_i32_e64 s[0:1], v64, v6
	s_or_b64 s[0:1], vcc, s[0:1]
	v_or_b32_e32 v103, 2, v102
	v_writelane_b32 v253, s0, 50
	v_or_b32_e32 v124, 3, v102
	s_add_i32 s97, s72, 9
	v_writelane_b32 v253, s1, 51
	s_or_b32 s0, s72, 1
	v_lshl_or_b32 v65, s0, 4, v88
	v_writelane_b32 v253, s0, 52
	v_cmp_lt_i32_e32 vcc, v65, v95
	v_cmp_gt_i32_e64 s[0:1], v65, v6
	s_or_b64 s[0:1], vcc, s[0:1]
	v_or_b32_e32 v7, 1, v65
	v_writelane_b32 v253, s0, 53
	v_cmp_lt_i32_e32 vcc, v7, v95
	v_or_b32_e32 v66, 2, v65
	v_writelane_b32 v253, s1, 54
	v_cmp_ge_i32_e64 s[0:1], v65, v6
	s_or_b64 s[0:1], vcc, s[0:1]
	v_cmp_lt_i32_e32 vcc, v66, v95
	v_writelane_b32 v253, s0, 55
	v_or_b32_e32 v67, 3, v65
	v_lshl_or_b32 v125, s97, 4, v88
	v_writelane_b32 v253, s1, 56
	v_cmp_gt_i32_e64 s[0:1], v66, v6
	s_or_b64 s[0:1], vcc, s[0:1]
	v_cmp_lt_i32_e32 vcc, v67, v95
	v_writelane_b32 v253, s0, 57
	v_or_b32_e32 v126, 2, v125
	v_or_b32_e32 v127, 3, v125
	v_writelane_b32 v253, s1, 58
	v_cmp_gt_i32_e64 s[0:1], v67, v6
	s_or_b64 s[0:1], vcc, s[0:1]
	v_or_b32_e32 v188, s7, v84
	v_writelane_b32 v253, s0, 59
	v_lshl_add_u64 v[36:37], v[26:27], 0, s[4:5]
	v_lshlrev_b64 v[90:91], 1, v[0:1]
	v_writelane_b32 v253, s1, 60
	s_add_i32 s0, s72, 2
	v_lshl_or_b32 v68, s0, 4, v88
	v_writelane_b32 v253, s0, 61
	v_cmp_lt_i32_e32 vcc, v68, v95
	v_cmp_gt_i32_e64 s[0:1], v68, v6
	s_or_b64 s[0:1], vcc, s[0:1]
	v_or_b32_e32 v7, 1, v68
	v_writelane_b32 v253, s0, 62
	v_cmp_lt_i32_e32 vcc, v7, v95
	v_or_b32_e32 v69, 2, v68
	v_writelane_b32 v253, s1, 63
	v_cmp_ge_i32_e64 s[0:1], v68, v6
	s_or_b64 s[0:1], vcc, s[0:1]
	v_cmp_lt_i32_e32 vcc, v69, v95
	v_writelane_b32 v254, s0, 0
	v_or_b32_e32 v70, 3, v68
	v_lshl_add_u64 v[14:15], v[14:15], 0, s[4:5]
	v_writelane_b32 v254, s1, 1
	v_cmp_gt_i32_e64 s[0:1], v69, v6
	s_or_b64 s[0:1], vcc, s[0:1]
	v_cmp_lt_i32_e32 vcc, v70, v95
	v_writelane_b32 v254, s0, 2
	v_lshlrev_b64 v[92:93], 1, v[16:17]
	v_lshl_add_u64 v[22:23], v[22:23], 0, s[4:5]
	v_writelane_b32 v254, s1, 3
	v_cmp_gt_i32_e64 s[0:1], v70, v6
	s_or_b64 s[0:1], vcc, s[0:1]
	v_cmp_gt_u32_e64 s[2:3], 16, v38
	v_writelane_b32 v254, s0, 4
	v_add_u32_e32 v94, 0, v32
	v_lshlrev_b32_e32 v32, 3, v40
	v_writelane_b32 v254, s1, 5
	s_add_i32 s0, s72, 3
; __device__ __forceinline__ f32x4 mfma16(bf16x8 a, bf16x8 b, f32x4 c) { return __builtin_amdgcn_mfma_f32_16x16x32_bf16(a, b, c, 0, 0, 0); }
; __device__ __forceinline__ void attn_phase(int wv, const Args& a, LAS unsigned char* lds, int w, bool dmy) {
;     ...
;         const int lo2 = (wid & ~1) < 6 ? (wid & ~1) : 6;
;         f32x4 sT[10];
;         float mx = -INFINITY;
; #pragma unroll
;         for (int i = 0; i < 10; ++i) {
;             const int kt = lo2 + i, pkt = kt ^ px;
;             f32x4 ac = (f32x4){0.f, 0.f, 0.f, 0.f};
; #pragma unroll
;             for (int k4 = 0; k4 < 4; ++k4) ac = mfma16(lds_ld16(lds + AT_K + ((pkt * 16 + fr) * 136 + k4 * 32 + 8 * fq) * 2), qc[k4], ac);
; #pragma unroll
;             for (int rr = 0; rr < 4; ++rr) {
;                 const int ki = kt * 16 + 4 * fq + rr;
;                 const bool valid = (ki >= qi) && (ki <= qi + 128) && (n > 0 || ki >= 128);
;                 const float sv = valid ? ac[rr] * qscale : -INFINITY;
;                 ac[rr] = sv; mx = fmaxf(mx, sv);
	v_lshl_or_b32 v71, s0, 4, v88
	v_writelane_b32 v254, s0, 6
	v_cmp_lt_i32_e32 vcc, v71, v95
	v_cmp_gt_i32_e64 s[0:1], v71, v6
	s_or_b64 s[0:1], vcc, s[0:1]
	v_or_b32_e32 v7, 1, v71
	v_writelane_b32 v254, s0, 7
	v_cmp_lt_i32_e32 vcc, v7, v95
	v_or_b32_e32 v72, 2, v71
	v_writelane_b32 v254, s1, 8
	v_cmp_ge_i32_e64 s[0:1], v71, v6
	s_or_b64 s[0:1], vcc, s[0:1]
	v_cmp_lt_i32_e32 vcc, v72, v95
	v_writelane_b32 v254, s0, 9
	v_or_b32_e32 v73, 3, v71
	v_and_b32_e32 v32, 0x78, v32
	v_writelane_b32 v254, s1, 10
	v_cmp_gt_i32_e64 s[0:1], v72, v6
	s_or_b64 s[0:1], vcc, s[0:1]
	v_cmp_lt_i32_e32 vcc, v73, v95
	v_writelane_b32 v254, s0, 11
	v_or_b32_e32 v32, 0x80, v32
	v_mul_u32_u24_e32 v106, 0x108, v85
	v_writelane_b32 v254, s1, 12
	v_cmp_gt_i32_e64 s[0:1], v73, v6
	s_or_b64 s[0:1], vcc, s[0:1]
	v_add_u32_e32 v114, v94, v41
	v_writelane_b32 v254, s0, 13
	v_add_u32_e32 v115, v94, v33
	s_mov_b32 s4, 0
	v_writelane_b32 v254, s1, 14
	s_add_i32 s0, s72, 4
	v_lshl_or_b32 v74, s0, 4, v88
	v_writelane_b32 v254, s0, 15
	v_cmp_lt_i32_e32 vcc, v74, v95
	v_cmp_gt_i32_e64 s[0:1], v74, v6
	s_or_b64 s[0:1], vcc, s[0:1]
	v_or_b32_e32 v7, 1, v74
	v_writelane_b32 v254, s0, 16
	v_cmp_lt_i32_e32 vcc, v7, v95
	v_or_b32_e32 v75, 2, v74
	v_writelane_b32 v254, s1, 17
	v_cmp_ge_i32_e64 s[0:1], v74, v6
	s_or_b64 s[0:1], vcc, s[0:1]
	v_cmp_lt_i32_e32 vcc, v75, v95
	v_writelane_b32 v254, s0, 18
	v_or_b32_e32 v76, 3, v74
	v_cmp_lt_i32_e64 s[12:13], s68, v70
	v_writelane_b32 v254, s1, 19
	v_cmp_gt_i32_e64 s[0:1], v75, v6
	s_or_b64 s[0:1], vcc, s[0:1]
	v_cmp_lt_i32_e32 vcc, v76, v95
	v_writelane_b32 v254, s0, 20
	v_cmp_lt_i32_e64 s[14:15], s68, v71
	v_cmp_lt_i32_e64 s[18:19], s68, v72
	v_writelane_b32 v254, s1, 21
	v_cmp_gt_i32_e64 s[0:1], v76, v6
	s_or_b64 s[0:1], vcc, s[0:1]
	v_cmp_lt_i32_e64 s[20:21], s68, v73
	v_writelane_b32 v254, s0, 22
	v_cmp_lt_i32_e64 s[22:23], s68, v74
	v_cmp_lt_i32_e64 s[26:27], s68, v75
	v_writelane_b32 v254, s1, 23
	s_add_i32 s0, s72, 5
	v_lshl_or_b32 v77, s0, 4, v88
	v_writelane_b32 v254, s0, 24
	v_cmp_lt_i32_e32 vcc, v77, v95
	v_cmp_gt_i32_e64 s[0:1], v77, v6
	s_or_b64 s[0:1], vcc, s[0:1]
	v_or_b32_e32 v7, 1, v77
	v_writelane_b32 v254, s0, 25
	v_cmp_lt_i32_e32 vcc, v7, v95
	v_or_b32_e32 v78, 2, v77
	v_writelane_b32 v254, s1, 26
	v_cmp_ge_i32_e64 s[0:1], v77, v6
	s_or_b64 s[0:1], vcc, s[0:1]
	v_cmp_lt_i32_e32 vcc, v78, v95
	v_writelane_b32 v254, s0, 27
	v_or_b32_e32 v79, 3, v77
	v_cmp_lt_i32_e64 s[28:29], s68, v76
	v_writelane_b32 v254, s1, 28
	v_cmp_gt_i32_e64 s[0:1], v78, v6
	s_or_b64 s[0:1], vcc, s[0:1]
	v_cmp_lt_i32_e32 vcc, v79, v95
	v_writelane_b32 v254, s0, 29
	v_cmp_lt_i32_e64 s[30:31], s68, v77
	v_cmp_lt_i32_e64 s[36:37], s68, v78
	v_writelane_b32 v254, s1, 30
	v_cmp_gt_i32_e64 s[0:1], v79, v6
	s_or_b64 s[0:1], vcc, s[0:1]
	v_cmp_lt_i32_e64 s[38:39], s68, v79
	v_writelane_b32 v254, s0, 31
	v_cmp_lt_i32_e64 s[56:57], s68, v102
	v_cmp_lt_i32_e64 s[60:61], s68, v103
	v_writelane_b32 v254, s1, 32
	s_add_i32 s0, s72, 6
	v_lshl_or_b32 v80, s0, 4, v88
	v_writelane_b32 v254, s0, 33
	v_cmp_lt_i32_e32 vcc, v80, v95
	v_cmp_gt_i32_e64 s[0:1], v80, v6
	s_or_b64 s[0:1], vcc, s[0:1]
	v_or_b32_e32 v7, 1, v80
	v_writelane_b32 v254, s0, 34
	v_cmp_lt_i32_e32 vcc, v7, v95
	v_or_b32_e32 v81, 2, v80
	v_writelane_b32 v254, s1, 35
	v_cmp_ge_i32_e64 s[0:1], v80, v6
	s_or_b64 s[0:1], vcc, s[0:1]
	v_cmp_lt_i32_e32 vcc, v81, v95
	v_writelane_b32 v254, s0, 36
	v_or_b32_e32 v82, 3, v80
	v_cmp_lt_i32_e64 s[40:41], s68, v80
	v_writelane_b32 v254, s1, 37
	v_cmp_gt_i32_e64 s[0:1], v81, v6
	s_or_b64 s[0:1], vcc, s[0:1]
	v_cmp_lt_i32_e32 vcc, v82, v95
	v_writelane_b32 v254, s0, 38
	v_cmp_lt_i32_e64 s[44:45], s68, v81
	v_cmp_lt_i32_e64 s[46:47], s68, v82
	v_writelane_b32 v254, s1, 39
	v_cmp_gt_i32_e64 s[0:1], v82, v6
	s_or_b64 s[0:1], vcc, s[0:1]
	v_cmp_lt_i32_e64 s[62:63], s68, v124
	v_writelane_b32 v254, s0, 40
	v_cmp_lt_i32_e64 s[64:65], s68, v125
	s_nop 0
	v_writelane_b32 v254, s1, 41
	s_add_i32 s0, s72, 7
	v_lshl_or_b32 v83, s0, 4, v88
	v_writelane_b32 v254, s0, 42
	v_cmp_lt_i32_e32 vcc, v83, v95
	v_cmp_gt_i32_e64 s[0:1], v83, v6
	s_or_b64 s[0:1], vcc, s[0:1]
	v_or_b32_e32 v7, 1, v83
	v_writelane_b32 v254, s0, 43
	v_cmp_lt_i32_e32 vcc, v7, v95
	v_or_b32_e32 v100, 2, v83
	v_writelane_b32 v254, s1, 44
	v_cmp_ge_i32_e64 s[0:1], v83, v6
	s_or_b64 s[0:1], vcc, s[0:1]
	v_cmp_lt_i32_e32 vcc, v100, v95
	v_writelane_b32 v254, s0, 45
	v_or_b32_e32 v101, 3, v83
	v_or_b32_e32 v7, 1, v102
	v_writelane_b32 v254, s1, 46
	v_cmp_gt_i32_e64 s[0:1], v100, v6
	s_or_b64 s[0:1], vcc, s[0:1]
	v_cmp_lt_i32_e32 vcc, v101, v95
	v_writelane_b32 v254, s0, 47
	v_cmp_lt_i32_e64 s[48:49], s68, v83
	v_cmp_lt_i32_e64 s[52:53], s68, v100
	v_writelane_b32 v254, s1, 48
	v_cmp_gt_i32_e64 s[0:1], v101, v6
	s_or_b64 s[0:1], vcc, s[0:1]
	v_cmp_lt_i32_e32 vcc, v102, v95
	v_writelane_b32 v254, s0, 49
	v_cmp_lt_i32_e64 s[54:55], s68, v101
	s_nop 0
	v_writelane_b32 v254, s1, 50
	v_cmp_gt_i32_e64 s[0:1], v102, v6
	s_or_b64 s[0:1], vcc, s[0:1]
	v_cmp_lt_i32_e32 vcc, v7, v95
	v_writelane_b32 v254, s0, 51
	v_or_b32_e32 v7, 1, v125
	s_nop 0
	v_writelane_b32 v254, s1, 52
	v_cmp_ge_i32_e64 s[0:1], v102, v6
	s_or_b64 s[0:1], vcc, s[0:1]
	v_cmp_lt_i32_e32 vcc, v103, v95
	v_writelane_b32 v254, s0, 53
	s_nop 1
	v_writelane_b32 v254, s1, 54
	v_cmp_gt_i32_e64 s[0:1], v103, v6
	s_or_b64 s[0:1], vcc, s[0:1]
	v_cmp_lt_i32_e32 vcc, v124, v95
	v_writelane_b32 v254, s0, 55
	s_nop 1
	v_writelane_b32 v254, s1, 56
	v_cmp_gt_i32_e64 s[0:1], v124, v6
	s_or_b64 s[0:1], vcc, s[0:1]
	v_cmp_lt_i32_e32 vcc, v125, v95
	v_writelane_b32 v254, s0, 57
	s_nop 1
	v_writelane_b32 v254, s1, 58
	v_cmp_gt_i32_e64 s[0:1], v125, v6
	s_or_b64 s[0:1], vcc, s[0:1]
; __device__ __forceinline__ f32x4 mfma16(bf16x8 a, bf16x8 b, f32x4 c) { return __builtin_amdgcn_mfma_f32_16x16x32_bf16(a, b, c, 0, 0, 0); }
; #define AT_LOADQ(T) do { const size_t tq_ = (T).tb + (size_t)(128 * (T).n + qi) * (T).d; \
;         _Pragma("unroll") for (int k4_ = 0; k4_ < 4; ++k4_) qf[k4_] = *(const bf16x8*)(AQ + tq_ * ATW + (T).head * 128 + k4_ * 32 + 8 * fq); qs = HS[tq_ * 24 + (T).head]; } while (0)
; __device__ __forceinline__ void attn_phase(int wv, const Args& a, LAS unsigned char* lds, int w, bool dmy) {
;     ...
;     AttnIt T = attn_decode(12 * w);
;     if (T.n > 0) { AT_LOADBLK(T, T.n - 1); AT_WRITEBLK((T.n & 1) ^ 1); }
;     AT_LOADBLK(T, T.n); AT_LOADQ(T);
;     for (int it = 0; it < 12; ++it) {
;     ...
;         const int lo2 = (wid & ~1) < 6 ? (wid & ~1) : 6;
;         f32x4 sT[10];
;         float mx = -INFINITY;
; #pragma unroll
;         for (int i = 0; i < 10; ++i) {
;             const int kt = lo2 + i, pkt = kt ^ px;
;             f32x4 ac = (f32x4){0.f, 0.f, 0.f, 0.f};
; #pragma unroll
;             for (int k4 = 0; k4 < 4; ++k4) ac = mfma16(lds_ld16(lds + AT_K + ((pkt * 16 + fr) * 136 + k4 * 32 + 8 * fq) * 2), qc[k4], ac);
; #pragma unroll
;             for (int rr = 0; rr < 4; ++rr) {
;                 const int ki = kt * 16 + 4 * fq + rr;
;                 const bool valid = (ki >= qi) && (ki <= qi + 128) && (n > 0 || ki >= 128);
;                 const float sv = valid ? ac[rr] * qscale : -INFINITY;
;                 ac[rr] = sv; mx = fmaxf(mx, sv);
	v_cmp_lt_i32_e32 vcc, v7, v95
	v_writelane_b32 v254, s0, 59
	s_nop 1
	v_writelane_b32 v254, s1, 60
	v_cmp_ge_i32_e64 s[0:1], v125, v6
	s_or_b64 s[0:1], vcc, s[0:1]
	v_cmp_lt_i32_e32 vcc, v126, v95
	v_writelane_b32 v254, s0, 61
	s_nop 1
	v_writelane_b32 v254, s1, 62
	v_cmp_gt_i32_e64 s[0:1], v126, v6
	s_or_b64 s[0:1], vcc, s[0:1]
	v_cmp_lt_i32_e32 vcc, v127, v95
	v_writelane_b32 v254, s0, 63
	s_nop 1
	v_writelane_b32 v255, s1, 0
	v_cmp_gt_i32_e64 s[0:1], v127, v6
	s_or_b64 s[0:1], vcc, s[0:1]
	s_nop 0
	v_writelane_b32 v255, s0, 1
	s_nop 1
	v_writelane_b32 v255, s1, 2
	v_mad_u64_u32 v[6:7], s[0:1], v2, s80, v[18:19]
	v_mov_b32_e32 v2, v7
	v_mad_u64_u32 v[2:3], s[0:1], v3, s80, v[2:3]
	v_mov_b32_e32 v7, v2
	v_lshlrev_b64 v[2:3], s10, v[188:189]
	v_lshl_add_u64 v[2:3], v[2:3], 0, s[86:87]
	v_mad_u64_u32 v[26:27], s[0:1], v2, s80, v[12:13]
	v_mov_b32_e32 v2, v27
	v_mad_u64_u32 v[2:3], s[0:1], v3, s80, v[2:3]
	v_mad_u64_u32 v[42:43], s[0:1], v4, s80, v[18:19]
	v_mov_b32_e32 v27, v2
	v_mov_b32_e32 v0, v43
	v_lshl_add_u64 v[10:11], v[26:27], 0, v[90:91]
	v_mad_u64_u32 v[0:1], s[0:1], v5, s80, v[0:1]
	v_or_b32_e32 v188, 1, v188
	v_mov_b32_e32 v43, v0
	global_load_dwordx4 v[0:3], v[6:7], off
	s_nop 0
	global_load_dwordx4 v[4:7], v[42:43], off
	global_load_dword v120, v[8:9], off offset:48
	s_nop 0
	global_load_dwordx4 v[8:11], v[10:11], off
	s_nop 0
	global_load_dword v121, v[14:15], off offset:48
	v_lshlrev_b64 v[14:15], s10, v[188:189]
	v_lshl_add_u64 v[14:15], v[14:15], 0, s[86:87]
	v_mad_u64_u32 v[42:43], s[0:1], v14, s80, v[12:13]
	v_mad_u64_u32 v[44:45], s[0:1], v20, s80, v[18:19]
	v_mov_b32_e32 v12, v43
	v_mov_b32_e32 v14, v45
	v_mad_u64_u32 v[12:13], s[0:1], v15, s80, v[12:13]
	v_mad_u64_u32 v[14:15], s[0:1], v21, s80, v[14:15]
	v_mad_u64_u32 v[20:21], s[0:1], v24, s80, v[18:19]
	v_mov_b32_e32 v16, v21
	v_mov_b32_e32 v43, v12
	v_mad_u64_u32 v[16:17], s[0:1], v25, s80, v[16:17]
	v_lshl_add_u64 v[12:13], v[42:43], 0, v[90:91]
	v_mov_b32_e32 v45, v14
	v_lshl_add_u64 v[26:27], v[26:27], 0, v[92:93]
	v_mov_b32_e32 v21, v16
	global_load_dwordx4 v[12:15], v[12:13], off
	s_nop 0
	global_load_dword v122, v[22:23], off offset:48
	global_load_dwordx4 v[16:19], v[44:45], off
	s_nop 0
	global_load_dwordx4 v[20:23], v[20:21], off
	s_nop 0
	global_load_dwordx4 v[24:27], v[26:27], off
	s_nop 0
	global_load_dword v123, v[28:29], off offset:48
	v_lshl_add_u64 v[28:29], v[42:43], 0, v[92:93]
	v_and_b32_e32 v188, 48, v38
	v_lshl_add_u64 v[44:45], v[30:31], 0, v[188:189]
	global_load_dwordx4 v[28:31], v[28:29], off
	s_nop 0
	global_load_dwordx4 v[60:63], v[44:45], off
	global_load_dwordx4 v[56:59], v[44:45], off offset:64
	global_load_dwordx4 v[52:55], v[44:45], off offset:128
	global_load_dwordx4 v[48:51], v[44:45], off offset:192
	global_load_dword v99, v[36:37], off
	v_writelane_b32 v255, s2, 3
	s_movk_i32 s0, 0x108
	v_mul_lo_u32 v105, v34, s0
	v_writelane_b32 v255, s3, 4
	v_cmp_lt_i32_e64 s[2:3], s68, v46
	v_mov_b32_e32 v34, 0x1080
	v_mad_u32_u24 v107, v85, s0, v34
	v_writelane_b32 v255, s2, 5
	v_mov_b32_e32 v34, 0x2100
	v_mad_u32_u24 v108, v85, s0, v34
	v_writelane_b32 v255, s3, 6
	s_movk_i32 s2, 0x7e
	v_cmp_lt_i32_e64 s[6:7], s2, v46
	v_mov_b32_e32 v34, 0x3180
	v_lshlrev_b32_e32 v42, 3, v35
	v_writelane_b32 v255, s6, 7
	v_and_b32_e32 v35, 48, v40
	v_add_u32_e32 v36, 0x200, v39
	v_writelane_b32 v255, s7, 8
	v_cmp_lt_i32_e64 s[6:7], s68, v47
	v_add_u32_e32 v37, 0x400, v39
	v_add_u32_e32 v39, 0x600, v39
	v_writelane_b32 v255, s6, 9
	v_mad_u32_u24 v109, v85, s0, v34
	v_mov_b32_e32 v34, 0x4200
	v_writelane_b32 v255, s7, 10
	v_cmp_lt_i32_e64 s[6:7], s68, v64
	v_add_u32_e32 v96, 0, v35
	v_lshlrev_b32_e32 v35, 2, v38
	v_writelane_b32 v255, s6, 11
	v_ashrrev_i32_e32 v36, 4, v36
	v_ashrrev_i32_e32 v37, 4, v37
	v_writelane_b32 v255, s7, 12
	v_cmp_lt_i32_e64 s[6:7], s68, v65
	v_ashrrev_i32_e32 v39, 4, v39
	v_mad_u32_u24 v110, v85, s0, v34
	v_writelane_b32 v255, s6, 13
	v_mov_b32_e32 v34, 0x5280
	v_xor_b32_e32 v97, 64, v35
	v_writelane_b32 v255, s7, 14
	v_cmp_lt_i32_e64 s[6:7], s2, v65
	v_xor_b32_e32 v104, 0x80, v35
	v_mul_lo_u32 v35, v89, s0
	v_writelane_b32 v255, s6, 15
	v_mul_lo_u32 v36, v36, s0
	v_mul_lo_u32 v37, v37, s0
	v_writelane_b32 v255, s7, 16
	v_cmp_lt_i32_e64 s[6:7], s68, v66
	v_mul_lo_u32 v39, v39, s0
	v_mad_u32_u24 v111, v85, s0, v34
	v_writelane_b32 v255, s6, 17
	v_mov_b32_e32 v34, 0x6300
	v_add_lshl_u32 v35, v32, v35, 1
	v_writelane_b32 v255, s7, 18
	v_cmp_lt_i32_e64 s[6:7], s68, v67
	v_add_lshl_u32 v36, v36, v32, 1
	v_add_lshl_u32 v37, v37, v32, 1
	v_writelane_b32 v255, s6, 19
	v_add_lshl_u32 v32, v39, v32, 1
	v_mad_u32_u24 v112, v85, s0, v34
	v_writelane_b32 v255, s7, 20
	v_cmp_lt_i32_e64 s[6:7], s68, v68
	v_mov_b32_e32 v34, 0x7380
	v_cmp_lt_i32_e64 s[16:17], s2, v71
	v_writelane_b32 v255, s6, 21
	v_cmp_lt_i32_e64 s[24:25], s2, v74
	v_cmp_lt_i32_e64 s[34:35], s2, v77
	v_writelane_b32 v255, s7, 22
	v_cmp_lt_i32_e64 s[6:7], s2, v68
	v_cmp_lt_i32_e64 s[42:43], s2, v80
	v_cmp_lt_i32_e64 s[50:51], s2, v83
	v_writelane_b32 v255, s6, 23
	v_cmp_lt_i32_e64 s[58:59], s2, v102
	v_cmp_lt_i32_e64 s[66:67], s2, v125
	v_writelane_b32 v255, s7, 24
	v_cmp_lt_i32_e64 s[6:7], s68, v69
	s_movk_i32 s2, 0x7f
	v_mad_u32_u24 v113, v85, s0, v34
	v_writelane_b32 v255, s6, 25
	v_add_u32_e32 v116, s94, v35
	v_add_u32_e32 v117, s94, v36
	v_add_u32_e32 v118, s94, v37
	v_add_u32_e32 v119, s94, v32
	v_lshlrev_b32_e32 v98, 1, v42
	v_readlane_b32 s1, v252, 22
	v_readlane_b32 s0, v252, 28
	v_writelane_b32 v255, s7, 26
	v_cmp_lt_i32_e64 s[68:69], s68, v126
	v_cmp_lt_i32_e64 s[70:71], s2, v127
	s_mov_b32 s80, s82
	s_waitcnt vmcnt(0)
	s_branch .LBB0_653
.LBB0_652:
	s_or_b64 exec, exec, s[86:87]
	s_add_i32 s4, s4, 1
	s_waitcnt vmcnt(8)
	v_mov_b64_e32 v[50:51], v[46:47]
	v_mov_b64_e32 v[54:55], v[42:43]
	v_mov_b64_e32 v[58:59], v[38:39]
	v_mov_b64_e32 v[62:63], v[34:35]
	s_cmp_lg_u32 s4, 12
	v_mov_b64_e32 v[48:49], v[44:45]
	v_mov_b64_e32 v[52:53], v[40:41]
	v_mov_b64_e32 v[56:57], v[36:37]
	v_mov_b64_e32 v[60:61], v[32:33]
	s_mov_b64 s[86:87], s[84:85]
	s_mov_b32 s80, s82
	s_mov_b32 s1, s83
	s_mov_b32 s0, s5
	s_mov_b32 s81, s8
	s_mov_b32 s82, 0x40000
	s_mov_b32 s83, 0x18000
	s_mov_b32 s84, 0x10000
	s_mov_b32 s85, 0x8000
	s_mov_b32 s88, 0x48000
	s_mov_b32 s89, 0x50000
	s_mov_b64 s[90:91], 0x58000
	s_barrier
	s_cbranch_scc0 .LBB0_659

; __device__ __forceinline__ void attn_phase(int wv, const Args& a, LAS unsigned char* lds, int w, bool dmy) {
;     ...
;         AT_WRITEBLK(sl);
;         bf16x8 qc[4];
; #pragma unroll
;         for (int k4 = 0; k4 < 4; ++k4) qc[k4] = qf[k4];
;         const float qscale = rsqrtf(qs * (1.f / 128.f) + EPS) * 0.08838834764831845f;
;         const size_t tokq = T.tb + (size_t)(128 * n + qi) * T.d;
;         __syncthreads();
.LBB0_655:
	s_nop 0
	v_fmamk_f32 v32, v120, 0x3c000000, v226
	v_mul_f32_e32 v33, 0x4b800000, v32
	v_cmp_gt_f32_e32 vcc, s33, v32
	v_lshlrev_b32_e32 v34, 16, v1
	v_and_b32_e32 v35, 0xffff0000, v1
	v_cndmask_b32_e32 v32, v32, v33, vcc
	v_rsq_f32_e32 v32, v32
	v_lshlrev_b32_e32 v38, 16, v3
	v_and_b32_e32 v39, 0xffff0000, v3
	s_and_b32 s2, s0, 1
	v_mul_f32_e32 v33, 0x45800000, v32
	v_cndmask_b32_e32 v36, v32, v33, vcc
	v_lshlrev_b32_e32 v32, 16, v0
	v_and_b32_e32 v33, 0xffff0000, v0
	v_pk_mul_f32 v[32:33], v[36:37], v[32:33] op_sel_hi:[0,1]
	v_pk_mul_f32 v[34:35], v[36:37], v[34:35] op_sel_hi:[0,1]
	v_cvt_pk_bf16_f32 v32, v32, v33
	v_cvt_pk_bf16_f32 v33, v34, v35
	v_lshlrev_b32_e32 v34, 16, v2
	v_and_b32_e32 v35, 0xffff0000, v2
	v_pk_mul_f32 v[34:35], v[36:37], v[34:35] op_sel_hi:[0,1]
	v_pk_mul_f32 v[36:37], v[36:37], v[38:39] op_sel_hi:[0,1]
	v_cvt_pk_bf16_f32 v34, v34, v35
	v_cvt_pk_bf16_f32 v35, v36, v37
	s_nop 0
	v_fmamk_f32 v36, v121, 0x3c000000, v226
	v_mul_f32_e32 v37, 0x4b800000, v36
	v_cmp_gt_f32_e32 vcc, s33, v36
	s_lshl_b32 s3, s2, 7
	v_add_u32_e32 v40, s3, v89
	v_cndmask_b32_e32 v36, v36, v37, vcc
	v_rsq_f32_e32 v38, v36
	v_mad_u64_u32 v[36:37], s[6:7], v40, s11, v[94:95]
	ds_write_b128 v36, v[32:35]
	v_mul_f32_e32 v32, 0x45800000, v38
	v_cndmask_b32_e32 v38, v38, v32, vcc
	v_lshlrev_b32_e32 v32, 16, v4
	v_and_b32_e32 v33, 0xffff0000, v4
	v_lshlrev_b32_e32 v34, 16, v5
	v_and_b32_e32 v35, 0xffff0000, v5
	v_pk_mul_f32 v[32:33], v[38:39], v[32:33] op_sel_hi:[0,1]
	v_pk_mul_f32 v[34:35], v[38:39], v[34:35] op_sel_hi:[0,1]
	v_cvt_pk_bf16_f32 v32, v32, v33
	v_cvt_pk_bf16_f32 v33, v34, v35
	v_lshlrev_b32_e32 v34, 16, v6
	v_and_b32_e32 v35, 0xffff0000, v6
	v_pk_mul_f32 v[34:35], v[38:39], v[34:35] op_sel_hi:[0,1]
	v_cvt_pk_bf16_f32 v34, v34, v35
	s_nop 0
	v_fmamk_f32 v35, v122, 0x3c000000, v226
	v_mul_f32_e32 v37, 0x4b800000, v35
	v_cmp_gt_f32_e32 vcc, s33, v35
	v_lshlrev_b32_e32 v40, 16, v7
	v_and_b32_e32 v41, 0xffff0000, v7
	v_cndmask_b32_e32 v35, v35, v37, vcc
	v_rsq_f32_e32 v37, v35
	v_pk_mul_f32 v[38:39], v[38:39], v[40:41] op_sel_hi:[0,1]
	v_cvt_pk_bf16_f32 v35, v38, v39
	ds_write_b128 v36, v[32:35] offset:8704
	v_mul_f32_e32 v32, 0x45800000, v37
	v_cndmask_b32_e32 v38, v37, v32, vcc
	s_nop 0
	v_lshlrev_b32_e32 v32, 16, v16
	v_and_b32_e32 v33, 0xffff0000, v16
	v_lshlrev_b32_e32 v34, 16, v17
	v_and_b32_e32 v35, 0xffff0000, v17
	v_pk_mul_f32 v[32:33], v[38:39], v[32:33] op_sel_hi:[0,1]
	v_pk_mul_f32 v[34:35], v[38:39], v[34:35] op_sel_hi:[0,1]
	v_cvt_pk_bf16_f32 v32, v32, v33
	v_cvt_pk_bf16_f32 v33, v34, v35
	v_lshlrev_b32_e32 v34, 16, v18
	v_and_b32_e32 v35, 0xffff0000, v18
	v_pk_mul_f32 v[34:35], v[38:39], v[34:35] op_sel_hi:[0,1]
	v_cvt_pk_bf16_f32 v34, v34, v35
	s_nop 0
	v_fmamk_f32 v35, v123, 0x3c000000, v226
	v_mul_f32_e32 v37, 0x4b800000, v35
	v_cmp_gt_f32_e32 vcc, s33, v35
	v_lshlrev_b32_e32 v40, 16, v19
	v_and_b32_e32 v41, 0xffff0000, v19
	v_cndmask_b32_e32 v35, v35, v37, vcc
	v_rsq_f32_e32 v37, v35
	v_pk_mul_f32 v[38:39], v[38:39], v[40:41] op_sel_hi:[0,1]
	v_cvt_pk_bf16_f32 v35, v38, v39
	ds_write_b128 v36, v[32:35] offset:17408
	v_mul_f32_e32 v32, 0x45800000, v37
	v_cndmask_b32_e32 v38, v37, v32, vcc
	v_lshlrev_b32_e32 v32, 16, v20
	v_and_b32_e32 v33, 0xffff0000, v20
	v_lshlrev_b32_e32 v34, 16, v21
	v_and_b32_e32 v35, 0xffff0000, v21
	v_pk_mul_f32 v[32:33], v[38:39], v[32:33] op_sel_hi:[0,1]
	v_pk_mul_f32 v[34:35], v[38:39], v[34:35] op_sel_hi:[0,1]
	v_cvt_pk_bf16_f32 v32, v32, v33
	v_cvt_pk_bf16_f32 v33, v34, v35
	v_lshlrev_b32_e32 v34, 16, v22
	v_and_b32_e32 v35, 0xffff0000, v22
	v_lshlrev_b32_e32 v40, 16, v23
	v_and_b32_e32 v41, 0xffff0000, v23
	v_pk_mul_f32 v[34:35], v[38:39], v[34:35] op_sel_hi:[0,1]
	v_pk_mul_f32 v[38:39], v[38:39], v[40:41] op_sel_hi:[0,1]
	v_cvt_pk_bf16_f32 v34, v34, v35
	v_cvt_pk_bf16_f32 v35, v38, v39
	ds_write_b128 v36, v[32:35] offset:26112
	v_or_b32_e32 v32, s3, v84
	v_add_u32_e32 v32, v32, v105
	v_lshl_add_u32 v32, v32, 1, 0
	v_lshlrev_b32_e32 v33, 16, v12
	s_mov_b32 s3, 0xffff
	v_lshrrev_b32_e32 v34, 16, v8
	s_mov_b32 s5, 0xffff0000
	v_add_u32_e32 v32, 0x11000, v32
	v_and_or_b32 v33, v8, s3, v33
	v_and_or_b32 v34, v12, s5, v34
	ds_write2_b32 v32, v33, v34 offset1:132
	v_lshlrev_b32_e32 v33, 16, v13
	v_lshrrev_b32_e32 v34, 16, v9
	v_and_or_b32 v33, v9, s3, v33
	v_and_or_b32 v34, v13, s5, v34
	v_add_u32_e32 v35, 0x400, v32
	ds_write2_b32 v35, v33, v34 offset0:8 offset1:140
	v_lshlrev_b32_e32 v33, 16, v14
	v_lshrrev_b32_e32 v34, 16, v10
	v_and_or_b32 v33, v10, s3, v33
	v_and_or_b32 v34, v14, s5, v34
	v_add_u32_e32 v35, 0x800, v32
	ds_write2_b32 v35, v33, v34 offset0:16 offset1:148
	v_lshlrev_b32_e32 v33, 16, v15
	v_lshrrev_b32_e32 v34, 16, v11
	v_and_or_b32 v33, v11, s3, v33
	v_and_or_b32 v34, v15, s5, v34
	v_add_u32_e32 v35, 0xc00, v32
	ds_write2_b32 v35, v33, v34 offset0:24 offset1:156
	s_nop 0
	v_lshlrev_b32_e32 v33, 16, v28
	v_lshrrev_b32_e32 v34, 16, v24
	v_and_or_b32 v33, v24, s3, v33
	v_and_or_b32 v34, v28, s5, v34
	v_add_u32_e32 v35, 0x8400, v32
	ds_write2_b32 v35, v33, v34 offset1:132
	v_lshlrev_b32_e32 v33, 16, v29
	v_lshrrev_b32_e32 v34, 16, v25
	v_and_or_b32 v33, v25, s3, v33
	v_and_or_b32 v34, v29, s5, v34
	v_add_u32_e32 v35, 0x8800, v32
	ds_write2_b32 v35, v33, v34 offset0:8 offset1:140
	v_lshlrev_b32_e32 v33, 16, v30
	v_lshrrev_b32_e32 v34, 16, v26
	v_and_or_b32 v33, v26, s3, v33
	v_and_or_b32 v34, v30, s5, v34
	v_add_u32_e32 v35, 0x8c00, v32
	ds_write2_b32 v35, v33, v34 offset0:16 offset1:148
	v_lshlrev_b32_e32 v33, 16, v31
	v_lshrrev_b32_e32 v34, 16, v27
	v_and_or_b32 v33, v27, s3, v33
	v_and_or_b32 v34, v31, s5, v34
	v_add_u32_e32 v32, 0x9000, v32
	ds_write2_b32 v32, v33, v34 offset0:24 offset1:156
	s_nop 0
	v_fmamk_f32 v32, v99, 0x3c000000, v226
	v_mul_f32_e32 v33, 0x4b800000, v32
	v_cmp_gt_f32_e32 vcc, s33, v32
	v_mov_b64_e32 v[44:45], v[48:49]
	v_mov_b64_e32 v[40:41], v[52:53]
	v_cndmask_b32_e32 v64, v32, v33, vcc
	v_mov_b64_e32 v[36:37], v[56:57]
	v_mov_b64_e32 v[32:33], v[60:61]
	s_mov_b32 s8, s81
	s_cmp_eq_u32 s4, 11
	v_mov_b64_e32 v[46:47], v[50:51]
	v_mov_b64_e32 v[42:43], v[54:55]
	v_mov_b64_e32 v[38:39], v[58:59]
	v_mov_b64_e32 v[34:35], v[62:63]
	s_mov_b32 s5, s0
	s_mov_b32 s83, s1
	s_mov_b32 s82, s80
	s_mov_b64 s[84:85], s[86:87]
	s_waitcnt lgkmcnt(0)
	s_barrier
; #define AT_LOADQ(T) do { const size_t tq_ = (T).tb + (size_t)(128 * (T).n + qi) * (T).d; \
;         _Pragma("unroll") for (int k4_ = 0; k4_ < 4; ++k4_) qf[k4_] = *(const bf16x8*)(AQ + tq_ * ATW + (T).head * 128 + k4_ * 32 + 8 * fq); qs = HS[tq_ * 24 + (T).head]; } while (0)
; __device__ __forceinline__ void attn_phase(int wv, const Args& a, LAS unsigned char* lds, int w, bool dmy) {
;     ...
;         if (it < 11) { T = attn_decode(12 * w + it + 1);
;             AT_LOADBLK(T, T.n); AT_LOADQ(T); }
	s_cbranch_scc1 .LBB0_657
	v_readlane_b32 s3, v253, 8
	s_add_i32 s3, s3, s4
	s_and_b32 s5, s3, 63
	s_bfe_u32 s7, s3, 0x20006
	s_ashr_i32 s3, s3, 8
	s_mul_hi_i32 s6, s3, 0x55555556
	s_lshr_b32 s81, s6, 31
	s_add_i32 s6, s6, s81
	s_mul_i32 s81, s6, 3
	s_sub_i32 s3, s3, s81
	s_lshl_b32 s81, s3, 1
	s_lshr_b32 s82, 64, s81
	s_sub_i32 s83, 6, s81
	s_add_i32 s82, s82, -1
	s_lshr_b32 s83, s5, s83
	s_and_b32 s5, s82, s5
	s_lshl_b32 s3, s3, 2
	s_or_b32 s82, s3, s7
	s_ashr_i32 s7, s6, 31
	s_lshl_b32 s3, s5, 7
	s_lshl_b64 s[84:85], s[6:7], 13
	v_add_u32_e32 v16, s3, v89
	s_lshl_b32 s6, s82, 7
	s_ashr_i32 s7, s6, 31
	v_ashrrev_i32_e32 v17, 31, v16
	s_or_b32 s84, s84, s83
	s_lshl_b64 s[88:89], s[6:7], 1
	v_lshlrev_b64 v[0:1], s81, v[16:17]
	v_lshl_add_u64 v[18:19], v[86:87], 0, s[88:89]
	v_lshl_add_u64 v[0:1], v[0:1], 0, s[84:85]
	s_movk_i32 s10, 0xc00
	v_mad_u64_u32 v[2:3], s[90:91], v0, s10, v[18:19]
	v_mov_b32_e32 v4, v3
	v_mad_u64_u32 v[4:5], s[90:91], v1, s10, v[4:5]
	v_readlane_b32 s90, v253, 42
	v_readlane_b32 s91, v253, 43
	s_movk_i32 s9, 0x60
	v_mov_b32_e32 v3, v4
	v_mov_b64_e32 v[44:45], s[90:91]
	v_mad_u64_u32 v[4:5], s[90:91], v0, s9, v[44:45]
	s_ashr_i32 s83, s82, 31
	v_readlane_b32 s6, v253, 40
	v_mov_b32_e32 v0, v5
	s_add_u32 s6, s6, s88
	v_readlane_b32 s7, v253, 41
	v_mad_u64_u32 v[0:1], s[90:91], v1, s9, v[0:1]
	v_or_b32_e32 v188, s3, v84
	s_addc_u32 s7, s7, s89
	v_mov_b32_e32 v5, v0
	v_lshlrev_b64 v[0:1], s81, v[188:189]
	v_lshl_add_u64 v[0:1], v[0:1], 0, s[84:85]
	v_mov_b64_e32 v[12:13], s[6:7]
	v_mad_u64_u32 v[20:21], s[6:7], v0, s10, v[12:13]
	v_mov_b32_e32 v0, v21
	v_mad_u64_u32 v[0:1], s[6:7], v1, s10, v[0:1]
	v_mov_b32_e32 v21, v0
	v_add_u32_e32 v0, 32, v16
	v_ashrrev_i32_e32 v1, 31, v0
	v_lshlrev_b64 v[0:1], s81, v[0:1]
	s_lshl_b64 s[90:91], s[82:83], 2
	v_lshl_add_u64 v[14:15], v[0:1], 0, s[84:85]
	v_lshl_add_u64 v[8:9], v[4:5], 0, s[90:91]
	v_mad_u64_u32 v[4:5], s[6:7], v14, s10, v[18:19]
	v_mad_u64_u32 v[22:23], s[6:7], v14, s9, v[44:45]
	v_mov_b32_e32 v0, v5
	v_mov_b32_e32 v14, v23
	v_mad_u64_u32 v[0:1], s[6:7], v15, s10, v[0:1]
	v_mad_u64_u32 v[14:15], s[6:7], v15, s9, v[14:15]
	v_mov_b32_e32 v23, v14
	v_lshl_add_u64 v[10:11], v[20:21], 0, v[90:91]
	v_mov_b32_e32 v5, v0
	v_lshl_add_u64 v[14:15], v[22:23], 0, s[90:91]
	v_or_b32_e32 v188, 1, v188
	global_load_dwordx4 v[0:3], v[2:3], off
	s_nop 0
	global_load_dwordx4 v[4:7], v[4:5], off
	s_nop 0
	global_load_dword v120, v[8:9], off offset:48
	s_nop 0
	global_load_dwordx4 v[8:11], v[10:11], off
	s_nop 0
	global_load_dword v121, v[14:15], off offset:48
	v_lshlrev_b64 v[14:15], s81, v[188:189]
	v_lshl_add_u64 v[14:15], v[14:15], 0, s[84:85]
	v_mad_u64_u32 v[28:29], s[6:7], v14, s10, v[12:13]
	v_mov_b32_e32 v12, v29
	v_add_u32_e32 v14, 64, v16
	v_mad_u64_u32 v[12:13], s[6:7], v15, s10, v[12:13]
	v_ashrrev_i32_e32 v15, 31, v14
	v_lshlrev_b64 v[14:15], s81, v[14:15]
	v_lshl_add_u64 v[14:15], v[14:15], 0, s[84:85]
	v_mad_u64_u32 v[22:23], s[6:7], v14, s10, v[18:19]
	v_mov_b32_e32 v24, v23
	v_mad_u64_u32 v[24:25], s[6:7], v15, s10, v[24:25]
	v_mov_b32_e32 v23, v24
	v_mad_u64_u32 v[24:25], s[6:7], v14, s9, v[44:45]
	v_mov_b32_e32 v14, v25
	v_add_u32_e32 v16, 0x60, v16
	v_mad_u64_u32 v[14:15], s[6:7], v15, s9, v[14:15]
	v_ashrrev_i32_e32 v17, 31, v16
	v_mov_b32_e32 v29, v12
	v_mov_b32_e32 v25, v14
	v_lshlrev_b64 v[16:17], s81, v[16:17]
	v_lshl_add_u64 v[12:13], v[28:29], 0, v[90:91]
	v_lshl_add_u64 v[24:25], v[24:25], 0, s[90:91]
	v_lshl_add_u64 v[26:27], v[16:17], 0, s[84:85]
	global_load_dwordx4 v[12:15], v[12:13], off
	s_nop 0
	global_load_dword v122, v[24:25], off offset:48
	v_lshl_add_u64 v[24:25], v[20:21], 0, v[92:93]
	v_mad_u64_u32 v[20:21], s[6:7], v26, s10, v[18:19]
	v_mad_u64_u32 v[30:31], s[6:7], v26, s9, v[44:45]
	v_mov_b32_e32 v16, v21
	v_mov_b32_e32 v26, v31
	v_mad_u64_u32 v[16:17], s[6:7], v27, s10, v[16:17]
	v_mad_u64_u32 v[26:27], s[6:7], v27, s9, v[26:27]
	v_mov_b32_e32 v31, v26
	v_mov_b32_e32 v21, v16
	v_lshl_add_u64 v[30:31], v[30:31], 0, s[90:91]
	global_load_dwordx4 v[16:19], v[22:23], off
	s_nop 0
	global_load_dwordx4 v[20:23], v[20:21], off
	s_nop 0
	global_load_dwordx4 v[24:27], v[24:25], off
	s_nop 0
	global_load_dword v123, v[30:31], off offset:48
	v_add_u32_e32 v30, s3, v95
	v_ashrrev_i32_e32 v31, 31, v30
	v_lshlrev_b64 v[30:31], s81, v[30:31]
	v_lshl_add_u64 v[46:47], v[30:31], 0, s[84:85]
	v_mov_b64_e32 v[30:31], s[78:79]
	v_mad_u64_u32 v[30:31], s[6:7], v46, s10, v[30:31]
	v_mov_b32_e32 v32, v31
	v_mad_u64_u32 v[32:33], s[6:7], v47, s10, v[32:33]
	v_mov_b32_e32 v31, v32
	v_mad_u64_u32 v[44:45], s[6:7], v46, s9, v[44:45]
	v_lshl_add_u64 v[28:29], v[28:29], 0, v[92:93]
	v_lshl_add_u64 v[30:31], v[30:31], 0, s[88:89]
	v_mov_b32_e32 v99, v189
	v_mov_b32_e32 v46, v45
	v_lshl_add_u64 v[66:67], v[30:31], 0, v[98:99]
	global_load_dwordx4 v[28:31], v[28:29], off
	s_nop 0
	global_load_dwordx4 v[32:35], v[66:67], off
	global_load_dwordx4 v[36:39], v[66:67], off offset:64
	global_load_dwordx4 v[40:43], v[66:67], off offset:128
	v_mad_u64_u32 v[46:47], s[6:7], v47, s9, v[46:47]
	v_mov_b32_e32 v45, v46
	v_lshl_add_u64 v[68:69], v[44:45], 0, s[90:91]
	global_load_dwordx4 v[44:47], v[66:67], off offset:192
	global_load_dword v99, v[68:69], off
	s_lshl_b32 s83, 1, s81
